# GEMM K-loops (QKV, UT, gate/up): first iteration peeled with C=0 on first touch, the 128 accumulator-zeroing v_mov per tile removed; plus attention loop edits
# speedup vs baseline: 1.0299x; 1.0115x over previous
.LBB0_164:
	s_ashr_i32 s77, s76, 31
	s_lshl_b64 s[10:11], s[76:77], 19
	s_add_u32 s80, s56, s10
	s_addc_u32 s81, s57, s11
	s_and_b64 s[10:11], s[12:13], exec
	s_cselect_b32 s46, s81, s7
	s_cselect_b32 s77, s80, s6
	s_ashr_i32 s79, s78, 31
	s_lshl_b64 s[10:11], s[78:79], 19
	v_readlane_b32 s55, v244, 29
	s_add_u32 s82, s55, s10
	v_readlane_b32 s10, v244, 30
	s_addc_u32 s83, s10, s11
	s_and_b64 s[10:11], s[12:13], exec
	s_cselect_b32 s12, s83, s85
	s_cselect_b32 s13, s82, s84
	s_add_u32 s6, s6, 0x40080
	s_addc_u32 s7, s7, 0
	s_add_u32 s79, s84, 0x100
	s_addc_u32 s96, s85, 0
	s_mov_b32 s97, -2
	s_add_u32 s10, s6, 0xfffc0080
	s_addc_u32 s11, s7, -1
	s_cmp_eq_u32 s97, 12
	s_cselect_b32 s87, s46, s11
	s_cselect_b32 s86, s77, s10
	s_cselect_b32 s85, s12, s96
	s_cselect_b32 s84, s13, s79
	s_add_i32 s10, 0, 0x14000
	v_add_u32_e32 v144, s10, v147
	ds_read_b128 v[140:143], v150
	ds_read_b128 v[152:155], v150 offset:1024
	ds_read_b128 v[156:159], v150 offset:2048
	ds_read_b128 v[160:163], v150 offset:3072
	ds_read_b128 v[164:167], v144
	ds_read_b128 v[168:171], v144 offset:1024
	ds_read_b128 v[172:175], v144 offset:2048
	ds_read_b128 v[176:179], v144 offset:3072
	v_lshl_add_u64 v[144:145], s[6:7], 0, v[136:137]
	s_add_i32 m0, s59, 0xc000
	ds_read_b128 v[180:183], v149
	ds_read_b128 v[184:187], v149 offset:1024
	ds_read_b128 v[192:195], v149 offset:2048
	ds_read_b128 v[196:199], v149 offset:3072
	ds_read_b128 v[200:203], v149 offset:4096
	ds_read_b128 v[204:207], v149 offset:5120
	ds_read_b128 v[208:211], v149 offset:6144
	ds_read_b128 v[212:215], v149 offset:7168
	global_load_lds_dwordx4 v[144:145], off
	v_lshl_add_u64 v[144:145], s[6:7], 0, v[138:139]
	s_add_i32 m0, s59, 0xe000
	s_nop 0
	global_load_lds_dwordx4 v[144:145], off
	s_waitcnt vmcnt(8)
	s_waitcnt lgkmcnt(0)
	s_barrier
	s_setprio 1
	s_waitcnt lgkmcnt(0)
	v_mfma_f32_16x16x32_bf16 v[126:129], v[140:143], v[180:183], 0
	v_mfma_f32_16x16x32_bf16 v[122:125], v[156:159], v[180:183], 0
	v_mfma_f32_16x16x32_bf16 v[110:113], v[140:143], v[192:195], 0
	v_mfma_f32_16x16x32_bf16 v[106:109], v[156:159], v[192:195], 0
	v_mfma_f32_16x16x32_bf16 v[94:97], v[140:143], v[200:203], 0
	v_mfma_f32_16x16x32_bf16 v[90:93], v[156:159], v[200:203], 0
	v_mfma_f32_16x16x32_bf16 v[78:81], v[140:143], v[208:211], 0
	v_mfma_f32_16x16x32_bf16 v[74:77], v[156:159], v[208:211], 0
	v_mfma_f32_16x16x32_bf16 v[126:129], v[152:155], v[184:187], v[126:129]
	v_mfma_f32_16x16x32_bf16 v[122:125], v[160:163], v[184:187], v[122:125]
	v_mfma_f32_16x16x32_bf16 v[110:113], v[152:155], v[196:199], v[110:113]
	v_mfma_f32_16x16x32_bf16 v[106:109], v[160:163], v[196:199], v[106:109]
	v_mfma_f32_16x16x32_bf16 v[94:97], v[152:155], v[204:207], v[94:97]
	v_mfma_f32_16x16x32_bf16 v[90:93], v[160:163], v[204:207], v[90:93]
	v_mfma_f32_16x16x32_bf16 v[78:81], v[152:155], v[212:215], v[78:81]
	v_mfma_f32_16x16x32_bf16 v[74:77], v[160:163], v[212:215], v[74:77]
	s_setprio 0
	s_setprio 1
	v_mfma_f32_16x16x32_bf16 v[118:121], v[164:167], v[180:183], 0
	v_mfma_f32_16x16x32_bf16 v[114:117], v[172:175], v[180:183], 0
	v_mfma_f32_16x16x32_bf16 v[102:105], v[164:167], v[192:195], 0
	v_mfma_f32_16x16x32_bf16 v[98:101], v[172:175], v[192:195], 0
	v_mfma_f32_16x16x32_bf16 v[86:89], v[164:167], v[200:203], 0
	v_mfma_f32_16x16x32_bf16 v[82:85], v[172:175], v[200:203], 0
	v_mfma_f32_16x16x32_bf16 v[70:73], v[164:167], v[208:211], 0
	v_mfma_f32_16x16x32_bf16 v[66:69], v[172:175], v[208:211], 0
	v_mfma_f32_16x16x32_bf16 v[118:121], v[168:171], v[184:187], v[118:121]
	v_mfma_f32_16x16x32_bf16 v[114:117], v[176:179], v[184:187], v[114:117]
	v_mfma_f32_16x16x32_bf16 v[102:105], v[168:171], v[196:199], v[102:105]
	v_mfma_f32_16x16x32_bf16 v[98:101], v[176:179], v[196:199], v[98:101]
	v_mfma_f32_16x16x32_bf16 v[86:89], v[168:171], v[204:207], v[86:89]
	v_mfma_f32_16x16x32_bf16 v[82:85], v[176:179], v[204:207], v[82:85]
	v_mfma_f32_16x16x32_bf16 v[70:73], v[168:171], v[212:215], v[70:73]
	v_mfma_f32_16x16x32_bf16 v[66:69], v[176:179], v[212:215], v[66:69]
	s_setprio 0
	s_barrier
	s_add_i32 s11, s63, s58
	v_lshl_add_u64 v[144:145], s[84:85], 0, v[0:1]
	s_mov_b32 m0, s11
	ds_read_b128 v[180:183], v149 offset:16384
	ds_read_b128 v[184:187], v149 offset:17408
	ds_read_b128 v[192:195], v149 offset:18432
	ds_read_b128 v[196:199], v149 offset:19456
	ds_read_b128 v[200:203], v149 offset:20480
	ds_read_b128 v[204:207], v149 offset:21504
	ds_read_b128 v[208:211], v149 offset:22528
	ds_read_b128 v[212:215], v149 offset:23552
	global_load_lds_dwordx4 v[144:145], off
	s_add_i32 m0, s11, 0x2000
	s_add_u32 vcc_lo, s84, 0x40000
	v_lshl_add_u64 v[188:189], s[84:85], 0, v[134:135]
	s_addc_u32 vcc_hi, s85, 0
	s_add_i32 s11, s10, s58
	global_load_lds_dwordx4 v[188:189], off
	v_lshl_add_u64 v[216:217], vcc, 0, v[0:1]
	s_mov_b32 m0, s11
	v_lshl_add_u64 v[218:219], s[86:87], 0, v[132:133]
	global_load_lds_dwordx4 v[216:217], off
	v_lshl_add_u64 v[216:217], vcc, 0, v[134:135]
	s_add_i32 m0, s11, 0x2000
	s_nop 0
	global_load_lds_dwordx4 v[216:217], off
	v_lshl_add_u64 v[216:217], s[86:87], 0, v[130:131]
	s_mov_b32 m0, s59
	s_nop 0
	global_load_lds_dwordx4 v[216:217], off
	s_mov_b32 m0, s60
	s_nop 0
	global_load_lds_dwordx4 v[218:219], off
	s_waitcnt vmcnt(8)
	s_waitcnt lgkmcnt(0)
	s_barrier
	s_setprio 1
	s_waitcnt lgkmcnt(0)
	v_mfma_f32_16x16x32_bf16 v[62:65], v[140:143], v[180:183], 0
	v_mfma_f32_16x16x32_bf16 v[58:61], v[156:159], v[180:183], 0
	v_mfma_f32_16x16x32_bf16 v[46:49], v[140:143], v[192:195], 0
	v_mfma_f32_16x16x32_bf16 v[42:45], v[156:159], v[192:195], 0
	v_mfma_f32_16x16x32_bf16 v[30:33], v[140:143], v[200:203], 0
	v_mfma_f32_16x16x32_bf16 v[26:29], v[156:159], v[200:203], 0
	v_mfma_f32_16x16x32_bf16 v[14:17], v[140:143], v[208:211], 0
	v_mfma_f32_16x16x32_bf16 v[10:13], v[156:159], v[208:211], 0
	v_mfma_f32_16x16x32_bf16 v[62:65], v[152:155], v[184:187], v[62:65]
	v_mfma_f32_16x16x32_bf16 v[58:61], v[160:163], v[184:187], v[58:61]
	v_mfma_f32_16x16x32_bf16 v[46:49], v[152:155], v[196:199], v[46:49]
	v_mfma_f32_16x16x32_bf16 v[42:45], v[160:163], v[196:199], v[42:45]
	v_mfma_f32_16x16x32_bf16 v[30:33], v[152:155], v[204:207], v[30:33]
	v_mfma_f32_16x16x32_bf16 v[26:29], v[160:163], v[204:207], v[26:29]
	v_mfma_f32_16x16x32_bf16 v[14:17], v[152:155], v[212:215], v[14:17]
	v_mfma_f32_16x16x32_bf16 v[10:13], v[160:163], v[212:215], v[10:13]
	s_setprio 0
	s_setprio 1
	v_mfma_f32_16x16x32_bf16 v[54:57], v[164:167], v[180:183], 0
	v_mfma_f32_16x16x32_bf16 v[50:53], v[172:175], v[180:183], 0
	v_mfma_f32_16x16x32_bf16 v[38:41], v[164:167], v[192:195], 0
	v_mfma_f32_16x16x32_bf16 v[34:37], v[172:175], v[192:195], 0
	v_mfma_f32_16x16x32_bf16 v[22:25], v[164:167], v[200:203], 0
	v_mfma_f32_16x16x32_bf16 v[18:21], v[172:175], v[200:203], 0
	v_mfma_f32_16x16x32_bf16 v[6:9], v[164:167], v[208:211], 0
	v_mfma_f32_16x16x32_bf16 v[2:5], v[172:175], v[208:211], 0
	v_mfma_f32_16x16x32_bf16 v[54:57], v[168:171], v[184:187], v[54:57]
	v_mfma_f32_16x16x32_bf16 v[50:53], v[176:179], v[184:187], v[50:53]
	v_mfma_f32_16x16x32_bf16 v[38:41], v[168:171], v[196:199], v[38:41]
	v_mfma_f32_16x16x32_bf16 v[34:37], v[176:179], v[196:199], v[34:37]
	v_mfma_f32_16x16x32_bf16 v[22:25], v[168:171], v[204:207], v[22:25]
	v_mfma_f32_16x16x32_bf16 v[18:21], v[176:179], v[204:207], v[18:21]
	v_mfma_f32_16x16x32_bf16 v[6:9], v[168:171], v[212:215], v[6:9]
	v_mfma_f32_16x16x32_bf16 v[2:5], v[176:179], v[212:215], v[2:5]
	s_setprio 0
	s_barrier
	s_add_i32 s11, 0, 0x18000
	v_add_u32_e32 v151, s11, v147
	s_add_i32 s67, 0, 0x1c000
	ds_read_b128 v[140:143], v151
	ds_read_b128 v[152:155], v151 offset:1024
	ds_read_b128 v[156:159], v151 offset:2048
	ds_read_b128 v[160:163], v151 offset:3072
	v_add_u32_e32 v151, s67, v147
	ds_read_b128 v[164:167], v151
	ds_read_b128 v[168:171], v151 offset:1024
	ds_read_b128 v[172:175], v151 offset:2048
	ds_read_b128 v[176:179], v151 offset:3072
	s_add_u32 s86, s86, 0x40000
	s_addc_u32 s87, s87, 0
	s_mov_b32 m0, s61
	v_lshl_add_u64 v[240:241], s[86:87], 0, v[130:131]
	ds_read_b128 v[180:183], v149 offset:32768
	ds_read_b128 v[184:187], v149 offset:33792
	ds_read_b128 v[192:195], v149 offset:34816
	ds_read_b128 v[196:199], v149 offset:35840
	ds_read_b128 v[200:203], v149 offset:36864
	ds_read_b128 v[204:207], v149 offset:37888
	ds_read_b128 v[208:211], v149 offset:38912
	ds_read_b128 v[212:215], v149 offset:39936
	global_load_lds_dwordx4 v[240:241], off
	v_lshl_add_u64 v[240:241], s[86:87], 0, v[132:133]
	s_mov_b32 m0, s68
	s_nop 0
	global_load_lds_dwordx4 v[240:241], off
	s_waitcnt vmcnt(8)
	s_waitcnt lgkmcnt(0)
	s_barrier
	s_setprio 1
	s_waitcnt lgkmcnt(0)
	v_mfma_f32_16x16x32_bf16 v[126:129], v[140:143], v[180:183], v[126:129]
	v_mfma_f32_16x16x32_bf16 v[122:125], v[156:159], v[180:183], v[122:125]
	v_mfma_f32_16x16x32_bf16 v[110:113], v[140:143], v[192:195], v[110:113]
	v_mfma_f32_16x16x32_bf16 v[106:109], v[156:159], v[192:195], v[106:109]
	v_mfma_f32_16x16x32_bf16 v[94:97], v[140:143], v[200:203], v[94:97]
	v_mfma_f32_16x16x32_bf16 v[90:93], v[156:159], v[200:203], v[90:93]
	v_mfma_f32_16x16x32_bf16 v[78:81], v[140:143], v[208:211], v[78:81]
	v_mfma_f32_16x16x32_bf16 v[74:77], v[156:159], v[208:211], v[74:77]
	v_mfma_f32_16x16x32_bf16 v[126:129], v[152:155], v[184:187], v[126:129]
	v_mfma_f32_16x16x32_bf16 v[122:125], v[160:163], v[184:187], v[122:125]
	v_mfma_f32_16x16x32_bf16 v[110:113], v[152:155], v[196:199], v[110:113]
	v_mfma_f32_16x16x32_bf16 v[106:109], v[160:163], v[196:199], v[106:109]
	v_mfma_f32_16x16x32_bf16 v[94:97], v[152:155], v[204:207], v[94:97]
	v_mfma_f32_16x16x32_bf16 v[90:93], v[160:163], v[204:207], v[90:93]
	v_mfma_f32_16x16x32_bf16 v[78:81], v[152:155], v[212:215], v[78:81]
	v_mfma_f32_16x16x32_bf16 v[74:77], v[160:163], v[212:215], v[74:77]
	s_setprio 0
	s_setprio 1
	v_mfma_f32_16x16x32_bf16 v[118:121], v[164:167], v[180:183], v[118:121]
	v_mfma_f32_16x16x32_bf16 v[114:117], v[172:175], v[180:183], v[114:117]
	v_mfma_f32_16x16x32_bf16 v[102:105], v[164:167], v[192:195], v[102:105]
	v_mfma_f32_16x16x32_bf16 v[98:101], v[172:175], v[192:195], v[98:101]
	v_mfma_f32_16x16x32_bf16 v[86:89], v[164:167], v[200:203], v[86:89]
	v_mfma_f32_16x16x32_bf16 v[82:85], v[172:175], v[200:203], v[82:85]
	v_mfma_f32_16x16x32_bf16 v[70:73], v[164:167], v[208:211], v[70:73]
	v_mfma_f32_16x16x32_bf16 v[66:69], v[172:175], v[208:211], v[66:69]
	v_mfma_f32_16x16x32_bf16 v[118:121], v[168:171], v[184:187], v[118:121]
	v_mfma_f32_16x16x32_bf16 v[114:117], v[176:179], v[184:187], v[114:117]
	v_mfma_f32_16x16x32_bf16 v[102:105], v[168:171], v[196:199], v[102:105]
	v_mfma_f32_16x16x32_bf16 v[98:101], v[176:179], v[196:199], v[98:101]
	v_mfma_f32_16x16x32_bf16 v[86:89], v[168:171], v[204:207], v[86:89]
	v_mfma_f32_16x16x32_bf16 v[82:85], v[176:179], v[204:207], v[82:85]
	v_mfma_f32_16x16x32_bf16 v[70:73], v[168:171], v[212:215], v[70:73]
	v_mfma_f32_16x16x32_bf16 v[66:69], v[176:179], v[212:215], v[66:69]
	s_setprio 0
	s_barrier
	s_add_i32 s55, s11, s58
	v_lshl_add_u64 v[144:145], v[144:145], 0, s[50:51]
	s_mov_b32 m0, s55
	ds_read_b128 v[180:183], v149 offset:49152
	ds_read_b128 v[184:187], v149 offset:50176
	ds_read_b128 v[192:195], v149 offset:51200
	ds_read_b128 v[196:199], v149 offset:52224
	ds_read_b128 v[200:203], v149 offset:53248
	ds_read_b128 v[204:207], v149 offset:54272
	ds_read_b128 v[208:211], v149 offset:55296
	ds_read_b128 v[212:215], v149 offset:56320
	global_load_lds_dwordx4 v[144:145], off
	s_add_i32 m0, s55, 0x2000
	s_add_u32 s84, s84, 0x40080
	v_lshl_add_u64 v[144:145], v[188:189], 0, s[50:51]
	s_addc_u32 s85, s85, 0
	s_add_i32 s55, s67, s58
	global_load_lds_dwordx4 v[144:145], off
	v_lshl_add_u64 v[144:145], s[84:85], 0, v[0:1]
	s_mov_b32 m0, s55
	s_nop 0
	global_load_lds_dwordx4 v[144:145], off
	v_lshl_add_u64 v[144:145], s[84:85], 0, v[134:135]
	s_add_i32 m0, s55, 0x2000
	s_nop 0
	global_load_lds_dwordx4 v[144:145], off
	v_lshl_add_u64 v[144:145], v[216:217], 0, s[50:51]
	s_mov_b32 m0, s89
	s_nop 0
	global_load_lds_dwordx4 v[144:145], off
	v_lshl_add_u64 v[144:145], v[218:219], 0, s[50:51]
	s_mov_b32 m0, s90
	s_nop 0
	global_load_lds_dwordx4 v[144:145], off
	s_waitcnt vmcnt(8)
	s_waitcnt lgkmcnt(0)
	s_barrier
	s_setprio 1
	s_waitcnt lgkmcnt(0)
	v_mfma_f32_16x16x32_bf16 v[62:65], v[140:143], v[180:183], v[62:65]
	v_mfma_f32_16x16x32_bf16 v[58:61], v[156:159], v[180:183], v[58:61]
	v_mfma_f32_16x16x32_bf16 v[46:49], v[140:143], v[192:195], v[46:49]
	v_mfma_f32_16x16x32_bf16 v[42:45], v[156:159], v[192:195], v[42:45]
	v_mfma_f32_16x16x32_bf16 v[30:33], v[140:143], v[200:203], v[30:33]
	v_mfma_f32_16x16x32_bf16 v[26:29], v[156:159], v[200:203], v[26:29]
	v_mfma_f32_16x16x32_bf16 v[14:17], v[140:143], v[208:211], v[14:17]
	v_mfma_f32_16x16x32_bf16 v[10:13], v[156:159], v[208:211], v[10:13]
	v_mfma_f32_16x16x32_bf16 v[62:65], v[152:155], v[184:187], v[62:65]
	v_mfma_f32_16x16x32_bf16 v[58:61], v[160:163], v[184:187], v[58:61]
	v_mfma_f32_16x16x32_bf16 v[46:49], v[152:155], v[196:199], v[46:49]
	v_mfma_f32_16x16x32_bf16 v[42:45], v[160:163], v[196:199], v[42:45]
	v_mfma_f32_16x16x32_bf16 v[30:33], v[152:155], v[204:207], v[30:33]
	v_mfma_f32_16x16x32_bf16 v[26:29], v[160:163], v[204:207], v[26:29]
	v_mfma_f32_16x16x32_bf16 v[14:17], v[152:155], v[212:215], v[14:17]
	v_mfma_f32_16x16x32_bf16 v[10:13], v[160:163], v[212:215], v[10:13]
	s_setprio 0
	s_setprio 1
	v_mfma_f32_16x16x32_bf16 v[54:57], v[164:167], v[180:183], v[54:57]
	v_mfma_f32_16x16x32_bf16 v[50:53], v[172:175], v[180:183], v[50:53]
	v_mfma_f32_16x16x32_bf16 v[38:41], v[164:167], v[192:195], v[38:41]
	v_mfma_f32_16x16x32_bf16 v[34:37], v[172:175], v[192:195], v[34:37]
	v_mfma_f32_16x16x32_bf16 v[22:25], v[164:167], v[200:203], v[22:25]
	v_mfma_f32_16x16x32_bf16 v[18:21], v[172:175], v[200:203], v[18:21]
	v_mfma_f32_16x16x32_bf16 v[6:9], v[164:167], v[208:211], v[6:9]
	v_mfma_f32_16x16x32_bf16 v[2:5], v[172:175], v[208:211], v[2:5]
	v_mfma_f32_16x16x32_bf16 v[54:57], v[168:171], v[184:187], v[54:57]
	v_mfma_f32_16x16x32_bf16 v[50:53], v[176:179], v[184:187], v[50:53]
	v_mfma_f32_16x16x32_bf16 v[38:41], v[168:171], v[196:199], v[38:41]
	v_mfma_f32_16x16x32_bf16 v[34:37], v[176:179], v[196:199], v[34:37]
	v_mfma_f32_16x16x32_bf16 v[22:25], v[168:171], v[204:207], v[22:25]
	v_mfma_f32_16x16x32_bf16 v[18:21], v[176:179], v[204:207], v[18:21]
	v_mfma_f32_16x16x32_bf16 v[6:9], v[168:171], v[212:215], v[6:9]
	v_mfma_f32_16x16x32_bf16 v[2:5], v[176:179], v[212:215], v[2:5]
	s_setprio 0
	s_barrier
	s_add_i32 s97, s97, 2
	s_add_u32 s6, s6, 0x100
	s_addc_u32 s7, s7, 0
	s_add_u32 s79, s79, 0x100
	s_addc_u32 s96, s96, 0

.LBB0_215:
	s_lshl_b32 s12, s46, 5
	v_ashrrev_i32_e32 v17, 6, v140
	s_and_b32 s12, s12, 0x60
	v_and_b32_e32 v16, 15, v140
	v_lshlrev_b32_e32 v19, 10, v17
	s_lshr_b32 s13, s12, 3
	s_add_i32 m0, s57, 0x18000
	v_lshl_add_u64 v[8:9], v[8:9], 0, s[50:51]
	v_lshl_or_b32 v141, s61, 6, v16
	v_lshl_add_u32 v19, s61, 13, v19
	v_add_lshl_u32 v17, s13, v17, 10
	s_waitcnt vmcnt(2)
	s_barrier
	global_load_lds_dwordx4 v[8:9], off
	v_lshl_add_u64 v[6:7], v[6:7], 0, s[50:51]
	s_add_i32 m0, s57, 0x1a000
	s_add_i32 s13, s57, 0x8000
	s_add_i32 s61, s57, 0xa000
	global_load_lds_dwordx4 v[6:7], off
	v_lshl_add_u64 v[4:5], v[4:5], 0, s[50:51]
	s_mov_b32 m0, s13
	s_add_u32 s68, s70, 0x40080
	global_load_lds_dwordx4 v[4:5], off
	v_lshl_add_u64 v[2:3], v[2:3], 0, s[50:51]
	s_mov_b32 m0, s61
	s_addc_u32 s69, s71, 0
	global_load_lds_dwordx4 v[2:3], off
	s_add_i32 m0, s57, 0x1c000
	v_lshl_add_u64 v[2:3], s[68:69], 0, v[0:1]
	global_load_lds_dwordx4 v[2:3], off
	v_lshl_add_u64 v[2:3], s[68:69], 0, v[134:135]
	s_add_i32 m0, s57, 0x1e000
	v_readlane_b32 s55, v244, 6
	global_load_lds_dwordx4 v[2:3], off
	s_add_u32 s55, s2, s55
	s_addc_u32 s69, s3, 0
	s_add_u32 s68, s55, s33
	s_addc_u32 s69, s69, 0
	v_readlane_b32 s55, v244, 2
	v_lshlrev_b32_e32 v2, 14, v10
	s_add_u32 s2, s2, s55
	v_and_b32_e32 v2, 0xffff8000, v2
	s_addc_u32 s3, s3, 0
	v_lshl_add_u32 v2, v11, 11, v2
	v_and_b32_e32 v3, 1, v10
	v_lshl_or_b32 v2, v3, 6, v2
	s_add_u32 s2, s2, s33
	v_lshl_add_u32 v2, v12, 1, v2
	v_mov_b32_e32 v3, v1
	s_addc_u32 s3, s3, 0
	v_lshl_add_u64 v[136:137], s[2:3], 0, v[2:3]
	v_lshlrev_b32_e32 v2, 14, v13
	v_and_b32_e32 v2, 0xffff8000, v2
	v_lshl_add_u32 v2, v14, 11, v2
	v_and_b32_e32 v3, 1, v13
	v_and_b32_e32 v18, 48, v140
	v_lshl_or_b32 v2, v3, 6, v2
	v_lshl_or_b32 v16, v16, 6, v18
	v_lshlrev_b32_e32 v18, 2, v140
	v_lshl_add_u32 v2, v15, 1, v2
	v_mov_b32_e32 v3, v1
	v_and_b32_e32 v18, 32, v18
	s_waitcnt vmcnt(6)
	v_lshl_add_u64 v[138:139], s[2:3], 0, v[2:3]
	v_readlane_b32 s2, v244, 3
	v_bitop3_b32 v19, v16, v19, v18 bitop3:0xde
	s_add_u32 s33, s72, s2
	v_readlane_b32 s2, v244, 4
	v_bitop3_b32 v142, v17, v16, v18 bitop3:0xf6
	s_addc_u32 s76, s73, s2
	s_mov_b32 s77, -2
	s_mov_b64 s[2:3], 0
	v_add_u32_e32 v143, 0, v19
	v_readlane_b32 s91, v245, 4
	v_readlane_b32 s87, v244, 26
	s_movk_i32 s88, 0x600
	v_readlane_b32 s89, v244, 21
	s_mov_b32 s90, 0x46000000
	v_readlane_b32 s94, v244, 31
	s_barrier
	v_add_u32_e32 v156, s63, v142
	v_add_u32_e32 v172, s10, v142
	s_add_u32 s55, s68, s2
	ds_read_b128 v[144:147], v156
	ds_read_b128 v[148:151], v156 offset:1024
	ds_read_b128 v[152:155], v156 offset:2048
	ds_read_b128 v[156:159], v156 offset:3072
	ds_read_b128 v[160:163], v172
	ds_read_b128 v[164:167], v172 offset:1024
	ds_read_b128 v[168:171], v172 offset:2048
	ds_read_b128 v[172:175], v172 offset:3072
	s_addc_u32 s72, s69, s3
	s_add_u32 s55, s55, 0x500100
	s_addc_u32 s72, s72, 0
	s_add_u32 s78, s33, s2
	s_addc_u32 s73, s76, s3
	s_cmpk_eq_i32 s2, 0x700
	s_cselect_b32 s75, s5, s72
	s_cselect_b32 s74, s4, s55
	s_cselect_b32 s73, s71, s73
	s_cselect_b32 s72, s70, s78
	v_lshl_add_u64 v[188:189], v[136:137], 0, s[2:3]
	s_add_i32 m0, s57, 0xc000
	ds_read_b128 v[176:179], v143
	ds_read_b128 v[180:183], v143 offset:1024
	ds_read_b128 v[184:187], v143 offset:2048
	ds_read_b128 v[192:195], v143 offset:3072
	ds_read_b128 v[196:199], v143 offset:4096
	ds_read_b128 v[200:203], v143 offset:5120
	ds_read_b128 v[204:207], v143 offset:6144
	ds_read_b128 v[208:211], v143 offset:7168
	global_load_lds_dwordx4 v[188:189], off
	v_lshl_add_u64 v[188:189], v[138:139], 0, s[2:3]
	s_add_i32 m0, s57, 0xe000
	s_nop 0
	global_load_lds_dwordx4 v[188:189], off
	s_waitcnt vmcnt(8)
	s_waitcnt lgkmcnt(0)
	s_barrier
	s_setprio 1
	s_waitcnt lgkmcnt(0)
	v_mfma_f32_16x16x32_bf16 v[126:129], v[144:147], v[176:179], 0
	v_mfma_f32_16x16x32_bf16 v[122:125], v[152:155], v[176:179], 0
	v_mfma_f32_16x16x32_bf16 v[118:121], v[144:147], v[184:187], 0
	v_mfma_f32_16x16x32_bf16 v[110:113], v[152:155], v[184:187], 0
	v_mfma_f32_16x16x32_bf16 v[102:105], v[144:147], v[196:199], 0
	v_mfma_f32_16x16x32_bf16 v[94:97], v[152:155], v[196:199], 0
	v_mfma_f32_16x16x32_bf16 v[86:89], v[144:147], v[204:207], 0
	v_mfma_f32_16x16x32_bf16 v[78:81], v[152:155], v[204:207], 0
	v_mfma_f32_16x16x32_bf16 v[126:129], v[148:151], v[180:183], v[126:129]
	v_mfma_f32_16x16x32_bf16 v[122:125], v[156:159], v[180:183], v[122:125]
	v_mfma_f32_16x16x32_bf16 v[118:121], v[148:151], v[192:195], v[118:121]
	v_mfma_f32_16x16x32_bf16 v[110:113], v[156:159], v[192:195], v[110:113]
	v_mfma_f32_16x16x32_bf16 v[102:105], v[148:151], v[200:203], v[102:105]
	v_mfma_f32_16x16x32_bf16 v[94:97], v[156:159], v[200:203], v[94:97]
	v_mfma_f32_16x16x32_bf16 v[86:89], v[148:151], v[208:211], v[86:89]
	v_mfma_f32_16x16x32_bf16 v[78:81], v[156:159], v[208:211], v[78:81]
	s_setprio 0
	s_setprio 1
	v_mfma_f32_16x16x32_bf16 v[114:117], v[160:163], v[176:179], 0
	v_mfma_f32_16x16x32_bf16 v[106:109], v[168:171], v[176:179], 0
	v_mfma_f32_16x16x32_bf16 v[98:101], v[160:163], v[184:187], 0
	v_mfma_f32_16x16x32_bf16 v[90:93], v[168:171], v[184:187], 0
	v_mfma_f32_16x16x32_bf16 v[82:85], v[160:163], v[196:199], 0
	v_mfma_f32_16x16x32_bf16 v[74:77], v[168:171], v[196:199], 0
	v_mfma_f32_16x16x32_bf16 v[70:73], v[160:163], v[204:207], 0
	v_mfma_f32_16x16x32_bf16 v[66:69], v[168:171], v[204:207], 0
	v_mfma_f32_16x16x32_bf16 v[114:117], v[164:167], v[180:183], v[114:117]
	v_mfma_f32_16x16x32_bf16 v[106:109], v[172:175], v[180:183], v[106:109]
	v_mfma_f32_16x16x32_bf16 v[98:101], v[164:167], v[192:195], v[98:101]
	v_mfma_f32_16x16x32_bf16 v[90:93], v[172:175], v[192:195], v[90:93]
	v_mfma_f32_16x16x32_bf16 v[82:85], v[164:167], v[200:203], v[82:85]
	v_mfma_f32_16x16x32_bf16 v[74:77], v[172:175], v[200:203], v[74:77]
	v_mfma_f32_16x16x32_bf16 v[70:73], v[164:167], v[208:211], v[70:73]
	v_mfma_f32_16x16x32_bf16 v[66:69], v[172:175], v[208:211], v[66:69]
	s_setprio 0
	s_barrier
	s_add_i32 s55, s63, s56
	v_lshl_add_u64 v[188:189], s[72:73], 0, v[0:1]
	s_mov_b32 m0, s55
	ds_read_b128 v[176:179], v143 offset:16384
	ds_read_b128 v[180:183], v143 offset:17408
	ds_read_b128 v[184:187], v143 offset:18432
	ds_read_b128 v[192:195], v143 offset:19456
	ds_read_b128 v[196:199], v143 offset:20480
	ds_read_b128 v[200:203], v143 offset:21504
	ds_read_b128 v[204:207], v143 offset:22528
	ds_read_b128 v[208:211], v143 offset:23552
	global_load_lds_dwordx4 v[188:189], off
	s_add_i32 m0, s55, 0x2000
	s_add_u32 s78, s72, 0x40000
	v_lshl_add_u64 v[212:213], s[72:73], 0, v[134:135]
	s_addc_u32 s79, s73, 0
	s_add_i32 s55, s10, s56
	global_load_lds_dwordx4 v[212:213], off
	v_lshl_add_u64 v[214:215], s[78:79], 0, v[0:1]
	s_mov_b32 m0, s55
	v_lshl_add_u64 v[216:217], s[74:75], 0, v[132:133]
	global_load_lds_dwordx4 v[214:215], off
	v_lshl_add_u64 v[214:215], s[78:79], 0, v[134:135]
	s_add_i32 m0, s55, 0x2000
	s_nop 0
	global_load_lds_dwordx4 v[214:215], off
	v_lshl_add_u64 v[214:215], s[74:75], 0, v[130:131]
	s_mov_b32 m0, s57
	s_nop 0
	global_load_lds_dwordx4 v[214:215], off
	s_mov_b32 m0, s58
	s_nop 0
	global_load_lds_dwordx4 v[216:217], off
	s_waitcnt vmcnt(8)
	s_waitcnt lgkmcnt(0)
	s_barrier
	s_setprio 1
	s_waitcnt lgkmcnt(0)
	v_mfma_f32_16x16x32_bf16 v[62:65], v[144:147], v[176:179], 0
	v_mfma_f32_16x16x32_bf16 v[58:61], v[152:155], v[176:179], 0
	v_mfma_f32_16x16x32_bf16 v[54:57], v[144:147], v[184:187], 0
	v_mfma_f32_16x16x32_bf16 v[46:49], v[152:155], v[184:187], 0
	v_mfma_f32_16x16x32_bf16 v[38:41], v[144:147], v[196:199], 0
	v_mfma_f32_16x16x32_bf16 v[30:33], v[152:155], v[196:199], 0
	v_mfma_f32_16x16x32_bf16 v[22:25], v[144:147], v[204:207], 0
	v_mfma_f32_16x16x32_bf16 v[14:17], v[152:155], v[204:207], 0
	v_mfma_f32_16x16x32_bf16 v[62:65], v[148:151], v[180:183], v[62:65]
	v_mfma_f32_16x16x32_bf16 v[58:61], v[156:159], v[180:183], v[58:61]
	v_mfma_f32_16x16x32_bf16 v[54:57], v[148:151], v[192:195], v[54:57]
	v_mfma_f32_16x16x32_bf16 v[46:49], v[156:159], v[192:195], v[46:49]
	v_mfma_f32_16x16x32_bf16 v[38:41], v[148:151], v[200:203], v[38:41]
	v_mfma_f32_16x16x32_bf16 v[30:33], v[156:159], v[200:203], v[30:33]
	v_mfma_f32_16x16x32_bf16 v[22:25], v[148:151], v[208:211], v[22:25]
	v_mfma_f32_16x16x32_bf16 v[14:17], v[156:159], v[208:211], v[14:17]
	s_setprio 0
	s_setprio 1
	v_mfma_f32_16x16x32_bf16 v[50:53], v[160:163], v[176:179], 0
	v_mfma_f32_16x16x32_bf16 v[42:45], v[168:171], v[176:179], 0
	v_mfma_f32_16x16x32_bf16 v[34:37], v[160:163], v[184:187], 0
	v_mfma_f32_16x16x32_bf16 v[26:29], v[168:171], v[184:187], 0
	v_mfma_f32_16x16x32_bf16 v[18:21], v[160:163], v[196:199], 0
	v_mfma_f32_16x16x32_bf16 v[10:13], v[168:171], v[196:199], 0
	v_mfma_f32_16x16x32_bf16 v[6:9], v[160:163], v[204:207], 0
	v_mfma_f32_16x16x32_bf16 v[2:5], v[168:171], v[204:207], 0
	v_mfma_f32_16x16x32_bf16 v[50:53], v[164:167], v[180:183], v[50:53]
	v_mfma_f32_16x16x32_bf16 v[42:45], v[172:175], v[180:183], v[42:45]
	v_mfma_f32_16x16x32_bf16 v[34:37], v[164:167], v[192:195], v[34:37]
	v_mfma_f32_16x16x32_bf16 v[26:29], v[172:175], v[192:195], v[26:29]
	v_mfma_f32_16x16x32_bf16 v[18:21], v[164:167], v[200:203], v[18:21]
	v_mfma_f32_16x16x32_bf16 v[10:13], v[172:175], v[200:203], v[10:13]
	v_mfma_f32_16x16x32_bf16 v[6:9], v[164:167], v[208:211], v[6:9]
	v_mfma_f32_16x16x32_bf16 v[2:5], v[172:175], v[208:211], v[2:5]
	s_setprio 0
	s_barrier
	v_add_u32_e32 v156, s11, v142
	v_add_u32_e32 v172, s67, v142
	ds_read_b128 v[144:147], v156
	ds_read_b128 v[148:151], v156 offset:1024
	ds_read_b128 v[152:155], v156 offset:2048
	ds_read_b128 v[156:159], v156 offset:3072
	ds_read_b128 v[160:163], v172
	ds_read_b128 v[164:167], v172 offset:1024
	ds_read_b128 v[168:171], v172 offset:2048
	ds_read_b128 v[172:175], v172 offset:3072
	s_add_u32 s74, s74, 0x40000
	s_addc_u32 s75, s75, 0
	s_mov_b32 m0, s59
	v_lshl_add_u64 v[218:219], s[74:75], 0, v[130:131]
	ds_read_b128 v[176:179], v143 offset:32768
	ds_read_b128 v[180:183], v143 offset:33792
	ds_read_b128 v[184:187], v143 offset:34816
	ds_read_b128 v[192:195], v143 offset:35840
	ds_read_b128 v[196:199], v143 offset:36864
	ds_read_b128 v[200:203], v143 offset:37888
	ds_read_b128 v[204:207], v143 offset:38912
	ds_read_b128 v[208:211], v143 offset:39936
	global_load_lds_dwordx4 v[218:219], off
	v_lshl_add_u64 v[218:219], s[74:75], 0, v[132:133]
	s_mov_b32 m0, s60
	s_nop 0
	global_load_lds_dwordx4 v[218:219], off
	s_waitcnt vmcnt(8)
	s_waitcnt lgkmcnt(0)
	s_barrier
	s_setprio 1
	s_waitcnt lgkmcnt(0)
	v_mfma_f32_16x16x32_bf16 v[126:129], v[144:147], v[176:179], v[126:129]
	v_mfma_f32_16x16x32_bf16 v[122:125], v[152:155], v[176:179], v[122:125]
	v_mfma_f32_16x16x32_bf16 v[118:121], v[144:147], v[184:187], v[118:121]
	v_mfma_f32_16x16x32_bf16 v[110:113], v[152:155], v[184:187], v[110:113]
	v_mfma_f32_16x16x32_bf16 v[102:105], v[144:147], v[196:199], v[102:105]
	v_mfma_f32_16x16x32_bf16 v[94:97], v[152:155], v[196:199], v[94:97]
	v_mfma_f32_16x16x32_bf16 v[86:89], v[144:147], v[204:207], v[86:89]
	v_mfma_f32_16x16x32_bf16 v[78:81], v[152:155], v[204:207], v[78:81]
	v_mfma_f32_16x16x32_bf16 v[126:129], v[148:151], v[180:183], v[126:129]
	v_mfma_f32_16x16x32_bf16 v[122:125], v[156:159], v[180:183], v[122:125]
	v_mfma_f32_16x16x32_bf16 v[118:121], v[148:151], v[192:195], v[118:121]
	v_mfma_f32_16x16x32_bf16 v[110:113], v[156:159], v[192:195], v[110:113]
	v_mfma_f32_16x16x32_bf16 v[102:105], v[148:151], v[200:203], v[102:105]
	v_mfma_f32_16x16x32_bf16 v[94:97], v[156:159], v[200:203], v[94:97]
	v_mfma_f32_16x16x32_bf16 v[86:89], v[148:151], v[208:211], v[86:89]
	v_mfma_f32_16x16x32_bf16 v[78:81], v[156:159], v[208:211], v[78:81]
	s_setprio 0
	s_setprio 1
	v_mfma_f32_16x16x32_bf16 v[114:117], v[160:163], v[176:179], v[114:117]
	v_mfma_f32_16x16x32_bf16 v[106:109], v[168:171], v[176:179], v[106:109]
	v_mfma_f32_16x16x32_bf16 v[98:101], v[160:163], v[184:187], v[98:101]
	v_mfma_f32_16x16x32_bf16 v[90:93], v[168:171], v[184:187], v[90:93]
	v_mfma_f32_16x16x32_bf16 v[82:85], v[160:163], v[196:199], v[82:85]
	v_mfma_f32_16x16x32_bf16 v[74:77], v[168:171], v[196:199], v[74:77]
	v_mfma_f32_16x16x32_bf16 v[70:73], v[160:163], v[204:207], v[70:73]
	v_mfma_f32_16x16x32_bf16 v[66:69], v[168:171], v[204:207], v[66:69]
	v_mfma_f32_16x16x32_bf16 v[114:117], v[164:167], v[180:183], v[114:117]
	v_mfma_f32_16x16x32_bf16 v[106:109], v[172:175], v[180:183], v[106:109]
	v_mfma_f32_16x16x32_bf16 v[98:101], v[164:167], v[192:195], v[98:101]
	v_mfma_f32_16x16x32_bf16 v[90:93], v[172:175], v[192:195], v[90:93]
	v_mfma_f32_16x16x32_bf16 v[82:85], v[164:167], v[200:203], v[82:85]
	v_mfma_f32_16x16x32_bf16 v[74:77], v[172:175], v[200:203], v[74:77]
	v_mfma_f32_16x16x32_bf16 v[70:73], v[164:167], v[208:211], v[70:73]
	v_mfma_f32_16x16x32_bf16 v[66:69], v[172:175], v[208:211], v[66:69]
	s_setprio 0
	s_barrier
	s_add_i32 s55, s11, s56
	v_lshl_add_u64 v[188:189], v[188:189], 0, s[50:51]
	s_mov_b32 m0, s55
	ds_read_b128 v[176:179], v143 offset:49152
	ds_read_b128 v[180:183], v143 offset:50176
	ds_read_b128 v[184:187], v143 offset:51200
	ds_read_b128 v[192:195], v143 offset:52224
	ds_read_b128 v[196:199], v143 offset:53248
	ds_read_b128 v[200:203], v143 offset:54272
	ds_read_b128 v[204:207], v143 offset:55296
	ds_read_b128 v[208:211], v143 offset:56320
	global_load_lds_dwordx4 v[188:189], off
	s_add_i32 m0, s55, 0x2000
	s_add_u32 s72, s72, 0x40080
	v_lshl_add_u64 v[188:189], v[212:213], 0, s[50:51]
	s_addc_u32 s73, s73, 0
	s_add_i32 s55, s67, s56
	global_load_lds_dwordx4 v[188:189], off
	v_lshl_add_u64 v[188:189], s[72:73], 0, v[0:1]
	s_mov_b32 m0, s55
	s_nop 0
	global_load_lds_dwordx4 v[188:189], off
	v_lshl_add_u64 v[188:189], s[72:73], 0, v[134:135]
	s_add_i32 m0, s55, 0x2000
	s_nop 0
	global_load_lds_dwordx4 v[188:189], off
	v_lshl_add_u64 v[188:189], v[214:215], 0, s[50:51]
	s_mov_b32 m0, s13
	s_nop 0
	global_load_lds_dwordx4 v[188:189], off
	v_lshl_add_u64 v[188:189], v[216:217], 0, s[50:51]
	s_mov_b32 m0, s61
	s_nop 0
	global_load_lds_dwordx4 v[188:189], off
	s_waitcnt vmcnt(8)
	s_waitcnt lgkmcnt(0)
	s_barrier
	s_setprio 1
	s_waitcnt lgkmcnt(0)
	v_mfma_f32_16x16x32_bf16 v[62:65], v[144:147], v[176:179], v[62:65]
	v_mfma_f32_16x16x32_bf16 v[58:61], v[152:155], v[176:179], v[58:61]
	v_mfma_f32_16x16x32_bf16 v[54:57], v[144:147], v[184:187], v[54:57]
	v_mfma_f32_16x16x32_bf16 v[46:49], v[152:155], v[184:187], v[46:49]
	v_mfma_f32_16x16x32_bf16 v[38:41], v[144:147], v[196:199], v[38:41]
	v_mfma_f32_16x16x32_bf16 v[30:33], v[152:155], v[196:199], v[30:33]
	v_mfma_f32_16x16x32_bf16 v[22:25], v[144:147], v[204:207], v[22:25]
	v_mfma_f32_16x16x32_bf16 v[14:17], v[152:155], v[204:207], v[14:17]
	v_mfma_f32_16x16x32_bf16 v[62:65], v[148:151], v[180:183], v[62:65]
	v_mfma_f32_16x16x32_bf16 v[58:61], v[156:159], v[180:183], v[58:61]
	v_mfma_f32_16x16x32_bf16 v[54:57], v[148:151], v[192:195], v[54:57]
	v_mfma_f32_16x16x32_bf16 v[46:49], v[156:159], v[192:195], v[46:49]
	v_mfma_f32_16x16x32_bf16 v[38:41], v[148:151], v[200:203], v[38:41]
	v_mfma_f32_16x16x32_bf16 v[30:33], v[156:159], v[200:203], v[30:33]
	v_mfma_f32_16x16x32_bf16 v[22:25], v[148:151], v[208:211], v[22:25]
	v_mfma_f32_16x16x32_bf16 v[14:17], v[156:159], v[208:211], v[14:17]
	s_setprio 0
	s_setprio 1
	v_mfma_f32_16x16x32_bf16 v[50:53], v[160:163], v[176:179], v[50:53]
	v_mfma_f32_16x16x32_bf16 v[42:45], v[168:171], v[176:179], v[42:45]
	v_mfma_f32_16x16x32_bf16 v[34:37], v[160:163], v[184:187], v[34:37]
	v_mfma_f32_16x16x32_bf16 v[26:29], v[168:171], v[184:187], v[26:29]
	v_mfma_f32_16x16x32_bf16 v[18:21], v[160:163], v[196:199], v[18:21]
	v_mfma_f32_16x16x32_bf16 v[10:13], v[168:171], v[196:199], v[10:13]
	v_mfma_f32_16x16x32_bf16 v[6:9], v[160:163], v[204:207], v[6:9]
	v_mfma_f32_16x16x32_bf16 v[2:5], v[168:171], v[204:207], v[2:5]
	v_mfma_f32_16x16x32_bf16 v[50:53], v[164:167], v[180:183], v[50:53]
	v_mfma_f32_16x16x32_bf16 v[42:45], v[172:175], v[180:183], v[42:45]
	v_mfma_f32_16x16x32_bf16 v[34:37], v[164:167], v[192:195], v[34:37]
	v_mfma_f32_16x16x32_bf16 v[26:29], v[172:175], v[192:195], v[26:29]
	v_mfma_f32_16x16x32_bf16 v[18:21], v[164:167], v[200:203], v[18:21]
	v_mfma_f32_16x16x32_bf16 v[10:13], v[172:175], v[200:203], v[10:13]
	v_mfma_f32_16x16x32_bf16 v[6:9], v[164:167], v[208:211], v[6:9]
	v_mfma_f32_16x16x32_bf16 v[2:5], v[172:175], v[208:211], v[2:5]
	s_setprio 0
	s_barrier
	s_add_i32 s77, s77, 2
	s_add_u32 s2, s2, 0x100
	s_addc_u32 s3, s3, 0

.LBB0_882:
	s_ashr_i32 s9, s8, 31
	s_lshl_b64 s[76:77], s[8:9], 19
	s_add_u32 s76, s57, s76
	s_addc_u32 s77, s58, s77
	s_and_b64 s[78:79], s[12:13], exec
	s_cselect_b32 s9, s77, s81
	s_cselect_b32 s92, s76, s80
	s_ashr_i32 s75, s74, 31
	s_lshl_b64 s[78:79], s[74:75], 19
	s_add_u32 s78, s46, s78
	s_addc_u32 s79, s56, s79
	s_and_b64 s[12:13], s[12:13], exec
	s_cselect_b32 s12, s79, s83
	s_cselect_b32 s13, s78, s82
	s_add_u32 s80, s80, 0x40080
	s_addc_u32 s81, s81, 0
	s_add_u32 s75, s82, 0x100
	s_addc_u32 s93, s83, 0
	s_mov_b32 s94, -2
	v_add_u32_e32 v140, s63, v143
	ds_read_b128 v[146:149], v140
	ds_read_b128 v[150:153], v140 offset:1024
	ds_read_b128 v[154:157], v140 offset:2048
	ds_read_b128 v[158:161], v140 offset:3072
	v_add_u32_e32 v140, s10, v143
	ds_read_b128 v[162:165], v140
	ds_read_b128 v[166:169], v140 offset:1024
	ds_read_b128 v[170:173], v140 offset:2048
	ds_read_b128 v[174:177], v140 offset:3072
	s_add_u32 s55, s80, 0xfffc0080
	s_addc_u32 s82, s81, -1
	s_cmp_eq_u32 s94, 12
	s_cselect_b32 s85, s9, s82
	s_cselect_b32 s84, s92, s55
	s_cselect_b32 s83, s12, s93
	s_cselect_b32 s82, s13, s75
	v_lshl_add_u64 v[140:141], s[80:81], 0, v[136:137]
	s_add_i32 m0, s60, 0xc000
	ds_read_b128 v[178:181], v145
	ds_read_b128 v[182:185], v145 offset:1024
	ds_read_b128 v[186:189], v145 offset:2048
	ds_read_b128 v[192:195], v145 offset:3072
	ds_read_b128 v[196:199], v145 offset:4096
	ds_read_b128 v[200:203], v145 offset:5120
	ds_read_b128 v[204:207], v145 offset:6144
	ds_read_b128 v[208:211], v145 offset:7168
	global_load_lds_dwordx4 v[140:141], off
	v_lshl_add_u64 v[140:141], s[80:81], 0, v[138:139]
	s_add_i32 m0, s60, 0xe000
	s_nop 0
	global_load_lds_dwordx4 v[140:141], off
	s_waitcnt vmcnt(8)
	s_waitcnt lgkmcnt(0)
	s_barrier
	s_setprio 1
	s_waitcnt lgkmcnt(0)
	v_mfma_f32_16x16x32_bf16 v[126:129], v[146:149], v[178:181], 0
	v_mfma_f32_16x16x32_bf16 v[122:125], v[154:157], v[178:181], 0
	v_mfma_f32_16x16x32_bf16 v[110:113], v[146:149], v[186:189], 0
	v_mfma_f32_16x16x32_bf16 v[106:109], v[154:157], v[186:189], 0
	v_mfma_f32_16x16x32_bf16 v[94:97], v[146:149], v[196:199], 0
	v_mfma_f32_16x16x32_bf16 v[90:93], v[154:157], v[196:199], 0
	v_mfma_f32_16x16x32_bf16 v[78:81], v[146:149], v[204:207], 0
	v_mfma_f32_16x16x32_bf16 v[74:77], v[154:157], v[204:207], 0
	v_mfma_f32_16x16x32_bf16 v[126:129], v[150:153], v[182:185], v[126:129]
	v_mfma_f32_16x16x32_bf16 v[122:125], v[158:161], v[182:185], v[122:125]
	v_mfma_f32_16x16x32_bf16 v[110:113], v[150:153], v[192:195], v[110:113]
	v_mfma_f32_16x16x32_bf16 v[106:109], v[158:161], v[192:195], v[106:109]
	v_mfma_f32_16x16x32_bf16 v[94:97], v[150:153], v[200:203], v[94:97]
	v_mfma_f32_16x16x32_bf16 v[90:93], v[158:161], v[200:203], v[90:93]
	v_mfma_f32_16x16x32_bf16 v[78:81], v[150:153], v[208:211], v[78:81]
	v_mfma_f32_16x16x32_bf16 v[74:77], v[158:161], v[208:211], v[74:77]
	s_setprio 0
	s_setprio 1
	v_mfma_f32_16x16x32_bf16 v[118:121], v[162:165], v[178:181], 0
	v_mfma_f32_16x16x32_bf16 v[114:117], v[170:173], v[178:181], 0
	v_mfma_f32_16x16x32_bf16 v[102:105], v[162:165], v[186:189], 0
	v_mfma_f32_16x16x32_bf16 v[98:101], v[170:173], v[186:189], 0
	v_mfma_f32_16x16x32_bf16 v[86:89], v[162:165], v[196:199], 0
	v_mfma_f32_16x16x32_bf16 v[82:85], v[170:173], v[196:199], 0
	v_mfma_f32_16x16x32_bf16 v[70:73], v[162:165], v[204:207], 0
	v_mfma_f32_16x16x32_bf16 v[66:69], v[170:173], v[204:207], 0
	v_mfma_f32_16x16x32_bf16 v[118:121], v[166:169], v[182:185], v[118:121]
	v_mfma_f32_16x16x32_bf16 v[114:117], v[174:177], v[182:185], v[114:117]
	v_mfma_f32_16x16x32_bf16 v[102:105], v[166:169], v[192:195], v[102:105]
	v_mfma_f32_16x16x32_bf16 v[98:101], v[174:177], v[192:195], v[98:101]
	v_mfma_f32_16x16x32_bf16 v[86:89], v[166:169], v[200:203], v[86:89]
	v_mfma_f32_16x16x32_bf16 v[82:85], v[174:177], v[200:203], v[82:85]
	v_mfma_f32_16x16x32_bf16 v[70:73], v[166:169], v[208:211], v[70:73]
	v_mfma_f32_16x16x32_bf16 v[66:69], v[174:177], v[208:211], v[66:69]
	s_setprio 0
	s_barrier
	s_add_i32 s55, s63, s59
	v_lshl_add_u64 v[140:141], s[82:83], 0, v[0:1]
	s_mov_b32 m0, s55
	ds_read_b128 v[178:181], v145 offset:16384
	ds_read_b128 v[182:185], v145 offset:17408
	ds_read_b128 v[186:189], v145 offset:18432
	ds_read_b128 v[192:195], v145 offset:19456
	ds_read_b128 v[196:199], v145 offset:20480
	ds_read_b128 v[200:203], v145 offset:21504
	ds_read_b128 v[204:207], v145 offset:22528
	ds_read_b128 v[208:211], v145 offset:23552
	global_load_lds_dwordx4 v[140:141], off
	s_add_i32 m0, s55, 0x2000
	s_add_u32 s96, s82, 0x40000
	v_lshl_add_u64 v[212:213], s[82:83], 0, v[134:135]
	s_addc_u32 s97, s83, 0
	s_add_i32 s55, s10, s59
	global_load_lds_dwordx4 v[212:213], off
	v_lshl_add_u64 v[214:215], s[96:97], 0, v[0:1]
	s_mov_b32 m0, s55
	v_lshl_add_u64 v[216:217], s[84:85], 0, v[132:133]
	global_load_lds_dwordx4 v[214:215], off
	v_lshl_add_u64 v[214:215], s[96:97], 0, v[134:135]
	s_add_i32 m0, s55, 0x2000
	s_nop 0
	global_load_lds_dwordx4 v[214:215], off
	v_lshl_add_u64 v[214:215], s[84:85], 0, v[130:131]
	s_mov_b32 m0, s60
	s_nop 0
	global_load_lds_dwordx4 v[214:215], off
	s_mov_b32 m0, s61
	s_nop 0
	global_load_lds_dwordx4 v[216:217], off
	s_waitcnt vmcnt(8)
	s_waitcnt lgkmcnt(0)
	s_barrier
	s_setprio 1
	s_waitcnt lgkmcnt(0)
	v_mfma_f32_16x16x32_bf16 v[62:65], v[146:149], v[178:181], 0
	v_mfma_f32_16x16x32_bf16 v[58:61], v[154:157], v[178:181], 0
	v_mfma_f32_16x16x32_bf16 v[46:49], v[146:149], v[186:189], 0
	v_mfma_f32_16x16x32_bf16 v[42:45], v[154:157], v[186:189], 0
	v_mfma_f32_16x16x32_bf16 v[30:33], v[146:149], v[196:199], 0
	v_mfma_f32_16x16x32_bf16 v[26:29], v[154:157], v[196:199], 0
	v_mfma_f32_16x16x32_bf16 v[14:17], v[146:149], v[204:207], 0
	v_mfma_f32_16x16x32_bf16 v[10:13], v[154:157], v[204:207], 0
	v_mfma_f32_16x16x32_bf16 v[62:65], v[150:153], v[182:185], v[62:65]
	v_mfma_f32_16x16x32_bf16 v[58:61], v[158:161], v[182:185], v[58:61]
	v_mfma_f32_16x16x32_bf16 v[46:49], v[150:153], v[192:195], v[46:49]
	v_mfma_f32_16x16x32_bf16 v[42:45], v[158:161], v[192:195], v[42:45]
	v_mfma_f32_16x16x32_bf16 v[30:33], v[150:153], v[200:203], v[30:33]
	v_mfma_f32_16x16x32_bf16 v[26:29], v[158:161], v[200:203], v[26:29]
	v_mfma_f32_16x16x32_bf16 v[14:17], v[150:153], v[208:211], v[14:17]
	v_mfma_f32_16x16x32_bf16 v[10:13], v[158:161], v[208:211], v[10:13]
	s_setprio 0
	s_setprio 1
	v_mfma_f32_16x16x32_bf16 v[54:57], v[162:165], v[178:181], 0
	v_mfma_f32_16x16x32_bf16 v[50:53], v[170:173], v[178:181], 0
	v_mfma_f32_16x16x32_bf16 v[38:41], v[162:165], v[186:189], 0
	v_mfma_f32_16x16x32_bf16 v[34:37], v[170:173], v[186:189], 0
	v_mfma_f32_16x16x32_bf16 v[22:25], v[162:165], v[196:199], 0
	v_mfma_f32_16x16x32_bf16 v[18:21], v[170:173], v[196:199], 0
	v_mfma_f32_16x16x32_bf16 v[6:9], v[162:165], v[204:207], 0
	v_mfma_f32_16x16x32_bf16 v[2:5], v[170:173], v[204:207], 0
	v_mfma_f32_16x16x32_bf16 v[54:57], v[166:169], v[182:185], v[54:57]
	v_mfma_f32_16x16x32_bf16 v[50:53], v[174:177], v[182:185], v[50:53]
	v_mfma_f32_16x16x32_bf16 v[38:41], v[166:169], v[192:195], v[38:41]
	v_mfma_f32_16x16x32_bf16 v[34:37], v[174:177], v[192:195], v[34:37]
	v_mfma_f32_16x16x32_bf16 v[22:25], v[166:169], v[200:203], v[22:25]
	v_mfma_f32_16x16x32_bf16 v[18:21], v[174:177], v[200:203], v[18:21]
	v_mfma_f32_16x16x32_bf16 v[6:9], v[166:169], v[208:211], v[6:9]
	v_mfma_f32_16x16x32_bf16 v[2:5], v[174:177], v[208:211], v[2:5]
	s_setprio 0
	s_barrier
	v_add_u32_e32 v158, s11, v143
	v_add_u32_e32 v174, s67, v143
	ds_read_b128 v[146:149], v158
	ds_read_b128 v[150:153], v158 offset:1024
	ds_read_b128 v[154:157], v158 offset:2048
	ds_read_b128 v[158:161], v158 offset:3072
	ds_read_b128 v[162:165], v174
	ds_read_b128 v[166:169], v174 offset:1024
	ds_read_b128 v[170:173], v174 offset:2048
	ds_read_b128 v[174:177], v174 offset:3072
	s_add_u32 s84, s84, 0x40000
	s_addc_u32 s85, s85, 0
	s_mov_b32 m0, s68
	v_lshl_add_u64 v[218:219], s[84:85], 0, v[130:131]
	ds_read_b128 v[178:181], v145 offset:32768
	ds_read_b128 v[182:185], v145 offset:33792
	ds_read_b128 v[186:189], v145 offset:34816
	ds_read_b128 v[192:195], v145 offset:35840
	ds_read_b128 v[196:199], v145 offset:36864
	ds_read_b128 v[200:203], v145 offset:37888
	ds_read_b128 v[204:207], v145 offset:38912
	ds_read_b128 v[208:211], v145 offset:39936
	global_load_lds_dwordx4 v[218:219], off
	v_lshl_add_u64 v[218:219], s[84:85], 0, v[132:133]
	s_mov_b32 m0, s69
	s_nop 0
	global_load_lds_dwordx4 v[218:219], off
	s_waitcnt vmcnt(8)
	s_waitcnt lgkmcnt(0)
	s_barrier
	s_setprio 1
	s_waitcnt lgkmcnt(0)
	v_mfma_f32_16x16x32_bf16 v[126:129], v[146:149], v[178:181], v[126:129]
	v_mfma_f32_16x16x32_bf16 v[122:125], v[154:157], v[178:181], v[122:125]
	v_mfma_f32_16x16x32_bf16 v[110:113], v[146:149], v[186:189], v[110:113]
	v_mfma_f32_16x16x32_bf16 v[106:109], v[154:157], v[186:189], v[106:109]
	v_mfma_f32_16x16x32_bf16 v[94:97], v[146:149], v[196:199], v[94:97]
	v_mfma_f32_16x16x32_bf16 v[90:93], v[154:157], v[196:199], v[90:93]
	v_mfma_f32_16x16x32_bf16 v[78:81], v[146:149], v[204:207], v[78:81]
	v_mfma_f32_16x16x32_bf16 v[74:77], v[154:157], v[204:207], v[74:77]
	v_mfma_f32_16x16x32_bf16 v[126:129], v[150:153], v[182:185], v[126:129]
	v_mfma_f32_16x16x32_bf16 v[122:125], v[158:161], v[182:185], v[122:125]
	v_mfma_f32_16x16x32_bf16 v[110:113], v[150:153], v[192:195], v[110:113]
	v_mfma_f32_16x16x32_bf16 v[106:109], v[158:161], v[192:195], v[106:109]
	v_mfma_f32_16x16x32_bf16 v[94:97], v[150:153], v[200:203], v[94:97]
	v_mfma_f32_16x16x32_bf16 v[90:93], v[158:161], v[200:203], v[90:93]
	v_mfma_f32_16x16x32_bf16 v[78:81], v[150:153], v[208:211], v[78:81]
	v_mfma_f32_16x16x32_bf16 v[74:77], v[158:161], v[208:211], v[74:77]
	s_setprio 0
	s_setprio 1
	v_mfma_f32_16x16x32_bf16 v[118:121], v[162:165], v[178:181], v[118:121]
	v_mfma_f32_16x16x32_bf16 v[114:117], v[170:173], v[178:181], v[114:117]
	v_mfma_f32_16x16x32_bf16 v[102:105], v[162:165], v[186:189], v[102:105]
	v_mfma_f32_16x16x32_bf16 v[98:101], v[170:173], v[186:189], v[98:101]
	v_mfma_f32_16x16x32_bf16 v[86:89], v[162:165], v[196:199], v[86:89]
	v_mfma_f32_16x16x32_bf16 v[82:85], v[170:173], v[196:199], v[82:85]
	v_mfma_f32_16x16x32_bf16 v[70:73], v[162:165], v[204:207], v[70:73]
	v_mfma_f32_16x16x32_bf16 v[66:69], v[170:173], v[204:207], v[66:69]
	v_mfma_f32_16x16x32_bf16 v[118:121], v[166:169], v[182:185], v[118:121]
	v_mfma_f32_16x16x32_bf16 v[114:117], v[174:177], v[182:185], v[114:117]
	v_mfma_f32_16x16x32_bf16 v[102:105], v[166:169], v[192:195], v[102:105]
	v_mfma_f32_16x16x32_bf16 v[98:101], v[174:177], v[192:195], v[98:101]
	v_mfma_f32_16x16x32_bf16 v[86:89], v[166:169], v[200:203], v[86:89]
	v_mfma_f32_16x16x32_bf16 v[82:85], v[174:177], v[200:203], v[82:85]
	v_mfma_f32_16x16x32_bf16 v[70:73], v[166:169], v[208:211], v[70:73]
	v_mfma_f32_16x16x32_bf16 v[66:69], v[174:177], v[208:211], v[66:69]
	s_setprio 0
	s_barrier
	s_add_i32 s55, s11, s59
	v_lshl_add_u64 v[140:141], v[140:141], 0, s[50:51]
	s_mov_b32 m0, s55
	ds_read_b128 v[178:181], v145 offset:49152
	ds_read_b128 v[182:185], v145 offset:50176
	ds_read_b128 v[186:189], v145 offset:51200
	ds_read_b128 v[192:195], v145 offset:52224
	ds_read_b128 v[196:199], v145 offset:53248
	ds_read_b128 v[200:203], v145 offset:54272
	ds_read_b128 v[204:207], v145 offset:55296
	ds_read_b128 v[208:211], v145 offset:56320
	global_load_lds_dwordx4 v[140:141], off
	s_add_i32 m0, s55, 0x2000
	s_add_u32 s82, s82, 0x40080
	v_lshl_add_u64 v[140:141], v[212:213], 0, s[50:51]
	s_addc_u32 s83, s83, 0
	s_add_i32 s55, s67, s59
	global_load_lds_dwordx4 v[140:141], off
	v_lshl_add_u64 v[140:141], s[82:83], 0, v[0:1]
	s_mov_b32 m0, s55
	s_nop 0
	global_load_lds_dwordx4 v[140:141], off
	v_lshl_add_u64 v[140:141], s[82:83], 0, v[134:135]
	s_add_i32 m0, s55, 0x2000
	s_nop 0
	global_load_lds_dwordx4 v[140:141], off
	v_lshl_add_u64 v[140:141], v[214:215], 0, s[50:51]
	s_mov_b32 m0, s86
	s_nop 0
	global_load_lds_dwordx4 v[140:141], off
	v_lshl_add_u64 v[140:141], v[216:217], 0, s[50:51]
	s_mov_b32 m0, s87
	s_nop 0
	global_load_lds_dwordx4 v[140:141], off
	s_waitcnt vmcnt(8)
	s_waitcnt lgkmcnt(0)
	s_barrier
	s_setprio 1
	s_waitcnt lgkmcnt(0)
	v_mfma_f32_16x16x32_bf16 v[62:65], v[146:149], v[178:181], v[62:65]
	v_mfma_f32_16x16x32_bf16 v[58:61], v[154:157], v[178:181], v[58:61]
	v_mfma_f32_16x16x32_bf16 v[46:49], v[146:149], v[186:189], v[46:49]
	v_mfma_f32_16x16x32_bf16 v[42:45], v[154:157], v[186:189], v[42:45]
	v_mfma_f32_16x16x32_bf16 v[30:33], v[146:149], v[196:199], v[30:33]
	v_mfma_f32_16x16x32_bf16 v[26:29], v[154:157], v[196:199], v[26:29]
	v_mfma_f32_16x16x32_bf16 v[14:17], v[146:149], v[204:207], v[14:17]
	v_mfma_f32_16x16x32_bf16 v[10:13], v[154:157], v[204:207], v[10:13]
	v_mfma_f32_16x16x32_bf16 v[62:65], v[150:153], v[182:185], v[62:65]
	v_mfma_f32_16x16x32_bf16 v[58:61], v[158:161], v[182:185], v[58:61]
	v_mfma_f32_16x16x32_bf16 v[46:49], v[150:153], v[192:195], v[46:49]
	v_mfma_f32_16x16x32_bf16 v[42:45], v[158:161], v[192:195], v[42:45]
	v_mfma_f32_16x16x32_bf16 v[30:33], v[150:153], v[200:203], v[30:33]
	v_mfma_f32_16x16x32_bf16 v[26:29], v[158:161], v[200:203], v[26:29]
	v_mfma_f32_16x16x32_bf16 v[14:17], v[150:153], v[208:211], v[14:17]
	v_mfma_f32_16x16x32_bf16 v[10:13], v[158:161], v[208:211], v[10:13]
	s_setprio 0
	s_setprio 1
	v_mfma_f32_16x16x32_bf16 v[54:57], v[162:165], v[178:181], v[54:57]
	v_mfma_f32_16x16x32_bf16 v[50:53], v[170:173], v[178:181], v[50:53]
	v_mfma_f32_16x16x32_bf16 v[38:41], v[162:165], v[186:189], v[38:41]
	v_mfma_f32_16x16x32_bf16 v[34:37], v[170:173], v[186:189], v[34:37]
	v_mfma_f32_16x16x32_bf16 v[22:25], v[162:165], v[196:199], v[22:25]
	v_mfma_f32_16x16x32_bf16 v[18:21], v[170:173], v[196:199], v[18:21]
	v_mfma_f32_16x16x32_bf16 v[6:9], v[162:165], v[204:207], v[6:9]
	v_mfma_f32_16x16x32_bf16 v[2:5], v[170:173], v[204:207], v[2:5]
	v_mfma_f32_16x16x32_bf16 v[54:57], v[166:169], v[182:185], v[54:57]
	v_mfma_f32_16x16x32_bf16 v[50:53], v[174:177], v[182:185], v[50:53]
	v_mfma_f32_16x16x32_bf16 v[38:41], v[166:169], v[192:195], v[38:41]
	v_mfma_f32_16x16x32_bf16 v[34:37], v[174:177], v[192:195], v[34:37]
	v_mfma_f32_16x16x32_bf16 v[22:25], v[166:169], v[200:203], v[22:25]
	v_mfma_f32_16x16x32_bf16 v[18:21], v[174:177], v[200:203], v[18:21]
	v_mfma_f32_16x16x32_bf16 v[6:9], v[166:169], v[208:211], v[6:9]
	v_mfma_f32_16x16x32_bf16 v[2:5], v[174:177], v[208:211], v[2:5]
	s_setprio 0
	s_barrier
	s_add_i32 s94, s94, 2
	s_add_u32 s80, s80, 0x100
	s_addc_u32 s81, s81, 0
	s_add_u32 s75, s75, 0x100
	s_addc_u32 s93, s93, 0
